# attention: row-sum v_pk_add_f32 block replaced by 32 scalar v_add_f32 interleaved 2 per QK MFMA (bit-identical association)
# speedup vs baseline: 1.0098x; 1.0098x over previous
; __device__ __forceinline__ void attn_unit(int h, int qb_, const Tensors& T, char* lds, LASP unsigned char* ldsl, int tid_in) {
;     ...
;       DMA_TILE(t + dist, sgd); sgd = sgd == NSTG - 1 ? 0 : sgd + 1;
;       if (t == NT - 1) {
; #pragma unroll
;         for (int qb = 0; qb < 2; ++qb)
; #pragma unroll
;           for (int ks = 0; ks < 2; ++ks) qr[qb][ks] = *reinterpret_cast<const bf16x8*>(Qw + 128 + qb * (16 * PITCH * 2) + ks * 64); }
.LBB0_569:
	s_min_u32 s4, s44, 0xfb
	s_add_i32 s4, s4, 4
	s_lshl_b32 s5, s4, 17
	s_and_b32 s28, s5, 0xfe0000
	s_add_u32 s5, s20, s28
	s_addc_u32 s29, s21, 0
	s_and_b32 s4, s4, 0x180
	s_add_u32 s4, s5, s4
	s_addc_u32 s5, s29, 0
	s_add_u32 s28, s22, s28
	s_addc_u32 s29, s23, 0
	s_mul_i32 s45, s42, 0x6000
	s_add_i32 s45, s45, 0
	v_lshl_add_u64 v[112:113], s[4:5], 0, v[176:177]
	s_add_i32 m0, s45, s17
	s_add_i32 s4, s45, s38
	global_load_lds_dwordx4 v[112:113], off
	v_lshl_add_u64 v[112:113], s[28:29], 0, v[144:145]
	s_add_i32 m0, s4, 0x2000
	s_nop 0
	global_load_lds_dwordx4 v[112:113], off
	v_lshl_add_u64 v[112:113], s[28:29], 0, v[146:147]
	s_add_i32 m0, s4, 0x2400
	s_cmpk_eq_i32 s44, 0x7f
	global_load_lds_dwordx4 v[112:113], off
	s_cselect_b64 s[28:29], -1, 0
	s_cmpk_lg_i32 s44, 0x7f
	s_cbranch_scc1 .LBB0_571
	global_load_dwordx4 v[4:7], v[148:149], off offset:128
	global_load_dwordx4 v[8:11], v[148:149], off offset:192
	global_load_dwordx4 v[12:15], v[150:151], off
	global_load_dwordx4 v[16:19], v[152:153], off
	s_waitcnt vmcnt(0)

; #define SBAR() __builtin_amdgcn_sched_barrier(0)
; #define MM16(A_, B_, C_) __builtin_amdgcn_mfma_f32_16x16x32_bf16(A_, B_, C_, 0, 0, 0)
; __device__ __forceinline__ void qkt2(f32x4a (&s)[4][2], const char* Ks, int ko0, int ko1, const bf16x8 (&qr)[2][2]) {
;   const f32x4a z4 = {0.f, 0.f, 0.f, 0.f};
; #pragma unroll
;   for (int h2 = 0; h2 < 2; ++h2) { bf16x8 kf[2][2];
; #pragma unroll
;     for (int k2 = 0; k2 < 2; ++k2) { kf[k2][0] = *reinterpret_cast<const bf16x8*>(Ks + ko0 + 2048 * (2 * h2 + k2)); kf[k2][1] = *reinterpret_cast<const bf16x8*>(Ks + ko1 + 2048 * (2 * h2 + k2)); }
;     SBAR();
; #pragma unroll
;     for (int k2 = 0; k2 < 2; ++k2)
; #pragma unroll
;       for (int qb = 0; qb < 2; ++qb) s[2 * h2 + k2][qb] = MM16(kf[k2][0], qr[qb][0], z4);
; #pragma unroll
;     for (int k2 = 0; k2 < 2; ++k2)
; #pragma unroll
;       for (int qb = 0; qb < 2; ++qb) s[2 * h2 + k2][qb] = MM16(kf[k2][1], qr[qb][1], s[2 * h2 + k2][qb]);
;     SBAR(); }
; __device__ __forceinline__ void finishSM(f32x4a (&s)[4][2], float& l0, float& l1, bf16x8 (&pa)[2][2]) {
;     ...
;   float a0 = 0.f, a1 = 0.f, a2 = 0.f, a3 = 0.f, b0 = 0.f, b1 = 0.f, b2 = 0.f, b3 = 0.f;
; #pragma unroll
;   for (int kb = 0; kb < 4; ++kb) { a0 += s[kb][0][0]; a1 += s[kb][0][1]; a2 += s[kb][0][2]; a3 += s[kb][0][3]; b0 += s[kb][1][0]; b1 += s[kb][1][1]; b2 += s[kb][1][2]; b3 += s[kb][1][3]; }
;   l0 += (a0 + a1) + (a2 + a3); l1 += (b0 + b1) + (b2 + b3);
.LBB0_573:
	s_mul_i32 s4, s43, 0x6000
	v_add_u32_e32 v238, s4, v232
	s_add_i32 s4, s43, 1
	s_cmp_lg_u32 s43, 5
	s_cselect_b32 s43, s4, 0
	s_setprio 1
	ds_read_b64_tr_b16 v[136:137], v238 offset:0
	ds_read_b64_tr_b16 v[138:139], v238 offset:0x200
	ds_read_b64_tr_b16 v[128:129], v238 offset:0x400
	ds_read_b64_tr_b16 v[130:131], v238 offset:0x600
	ds_read_b64_tr_b16 v[140:141], v238 offset:0x800
	ds_read_b64_tr_b16 v[142:143], v238 offset:0xa00
	ds_read_b64_tr_b16 v[132:133], v238 offset:0xc00
	ds_read_b64_tr_b16 v[134:135], v238 offset:0xe00
	s_cmpk_eq_i32 s44, 0xff
	s_cbranch_scc1 .LBB0_575
	s_mul_i32 s4, s43, 0x6000
	s_add_i32 s4, s4, 0
	v_add_u32_e32 v178, s4, v205
	v_add_u32_e32 v179, s4, v206
	ds_read_b128 v[56:59], v178
	ds_read_b128 v[60:63], v178 offset:2048
	ds_read_b128 v[64:67], v179
	ds_read_b128 v[68:71], v179 offset:2048
	s_waitcnt lgkmcnt(0)
	v_mfma_f32_16x16x32_bf16 v[80:83], v[56:59], v[4:7], 0
	v_add_f32_e32 v188, v188, v194
	v_add_f32_e32 v189, v189, v195
	v_mfma_f32_16x16x32_bf16 v[88:91], v[56:59], v[12:15], 0
	v_add_f32_e32 v184, v184, v192
	v_add_f32_e32 v185, v185, v193
	v_mfma_f32_16x16x32_bf16 v[92:95], v[60:63], v[4:7], 0
	v_add_f32_e32 v174, v174, v190
	v_add_f32_e32 v175, v175, v191
	v_mfma_f32_16x16x32_bf16 v[96:99], v[60:63], v[12:15], 0
	v_add_f32_e32 v170, v170, v186
	v_add_f32_e32 v171, v171, v187
	v_mfma_f32_16x16x32_bf16 v[56:59], v[64:67], v[8:11], v[80:83]
	v_add_f32_e32 v172, v172, v188
	v_add_f32_e32 v173, v173, v189
	v_mfma_f32_16x16x32_bf16 v[60:63], v[64:67], v[16:19], v[88:91]
	v_add_f32_e32 v168, v168, v184
	v_add_f32_e32 v169, v169, v185
	v_mfma_f32_16x16x32_bf16 v[64:67], v[68:71], v[8:11], v[92:95]
	v_add_f32_e32 v166, v166, v174
	v_add_f32_e32 v167, v167, v175
	v_mfma_f32_16x16x32_bf16 v[68:71], v[68:71], v[16:19], v[96:99]
	v_add_f32_e32 v162, v162, v170
	v_add_f32_e32 v163, v163, v171
	s_nop 0
	ds_read_b128 v[80:83], v178 offset:4096
	ds_read_b128 v[88:91], v178 offset:6144
	ds_read_b128 v[92:95], v179 offset:4096
	ds_read_b128 v[96:99], v179 offset:6144
	s_waitcnt lgkmcnt(3)
	v_mfma_f32_16x16x32_bf16 v[240:243], v[80:83], v[4:7], 0
	v_add_f32_e32 v164, v164, v172
	v_add_f32_e32 v165, v165, v173
	v_mfma_f32_16x16x32_bf16 v[244:247], v[80:83], v[12:15], 0
	v_add_f32_e32 v160, v160, v168
	v_add_f32_e32 v161, v161, v169
	s_waitcnt lgkmcnt(2)
	v_mfma_f32_16x16x32_bf16 v[248:251], v[88:91], v[4:7], 0
	v_add_f32_e32 v158, v158, v166
	v_add_f32_e32 v159, v159, v167
	v_mfma_f32_16x16x32_bf16 v[228:231], v[88:91], v[12:15], 0
	v_add_f32_e32 v156, v156, v162
	v_add_f32_e32 v157, v157, v163
	s_waitcnt lgkmcnt(1)
	v_mfma_f32_16x16x32_bf16 v[80:83], v[92:95], v[8:11], v[240:243]
	v_add_f32_e32 v160, v164, v160
	v_add_f32_e32 v161, v165, v161
	v_mfma_f32_16x16x32_bf16 v[88:91], v[92:95], v[16:19], v[244:247]
	v_add_f32_e32 v156, v158, v156
	v_add_f32_e32 v157, v159, v157
	s_waitcnt lgkmcnt(0)
	v_mfma_f32_16x16x32_bf16 v[92:95], v[96:99], v[8:11], v[248:251]
	v_add_f32_e32 v156, v160, v156
	v_add_f32_e32 v157, v161, v157
	v_mfma_f32_16x16x32_bf16 v[96:99], v[96:99], v[16:19], v[228:231]
	v_add_f32_e32 v154, v154, v156
	v_add_f32_e32 v155, v155, v157
	s_branch .LBB0_576
.LBB0_575:
	v_mov_b32_e32 v56, v195
	v_mov_b32_e32 v57, v193
	v_mov_b32_e32 v58, v191
	v_mov_b32_e32 v59, v187
	v_mov_b32_e32 v60, v194
	v_mov_b32_e32 v61, v192
	v_mov_b32_e32 v62, v190
	v_mov_b32_e32 v63, v186
	v_mov_b32_e32 v64, v189
	v_mov_b32_e32 v65, v185
	v_mov_b32_e32 v66, v175
	v_mov_b32_e32 v67, v171
	v_mov_b32_e32 v68, v188
	v_mov_b32_e32 v69, v184
	v_mov_b32_e32 v70, v174
	v_mov_b32_e32 v71, v170
	v_mov_b32_e32 v80, v173
	v_mov_b32_e32 v81, v169
	v_mov_b32_e32 v82, v167
	v_mov_b32_e32 v83, v163
	v_mov_b32_e32 v88, v172
	v_mov_b32_e32 v89, v168
	v_mov_b32_e32 v90, v166
	v_mov_b32_e32 v91, v162
	v_mov_b32_e32 v92, v165
	v_mov_b32_e32 v93, v161
	v_mov_b32_e32 v94, v159
	v_mov_b32_e32 v95, v157
	v_mov_b32_e32 v96, v164
	v_mov_b32_e32 v97, v160
	v_mov_b32_e32 v98, v158
	v_mov_b32_e32 v99, v156
	v_add_f32_e32 v188, v188, v194
	v_add_f32_e32 v189, v189, v195
	v_add_f32_e32 v184, v184, v192
	v_add_f32_e32 v185, v185, v193
	v_add_f32_e32 v174, v174, v190
	v_add_f32_e32 v175, v175, v191
	v_add_f32_e32 v170, v170, v186
	v_add_f32_e32 v171, v171, v187
	v_add_f32_e32 v172, v172, v188
	v_add_f32_e32 v173, v173, v189
	v_add_f32_e32 v168, v168, v184
	v_add_f32_e32 v169, v169, v185
	v_add_f32_e32 v166, v166, v174
	v_add_f32_e32 v167, v167, v175
	v_add_f32_e32 v162, v162, v170
	v_add_f32_e32 v163, v163, v171
	v_add_f32_e32 v164, v164, v172
	v_add_f32_e32 v165, v165, v173
	v_add_f32_e32 v160, v160, v168
	v_add_f32_e32 v161, v161, v169
	v_add_f32_e32 v158, v158, v166
	v_add_f32_e32 v159, v159, v167
	v_add_f32_e32 v156, v156, v162
	v_add_f32_e32 v157, v157, v163
	v_add_f32_e32 v160, v164, v160
	v_add_f32_e32 v161, v165, v161
	v_add_f32_e32 v156, v158, v156
	v_add_f32_e32 v157, v159, v157
	v_add_f32_e32 v156, v160, v156
	v_add_f32_e32 v157, v161, v157
	v_add_f32_e32 v154, v154, v156
	v_add_f32_e32 v155, v155, v157
; #define SBAR() __builtin_amdgcn_sched_barrier(0)
; #define MM16(A_, B_, C_) __builtin_amdgcn_mfma_f32_16x16x32_bf16(A_, B_, C_, 0, 0, 0)
; template <int OFF> __device__ __forceinline__ s16x4 tr_read(int vb) { s16x4 r; asm volatile("ds_read_b64_tr_b16 %0, %1 offset:%2" : "=&v"(r) : "v"(vb), "i"(OFF) : "memory"); return r; }
; #define LWAIT() do { asm volatile("s_waitcnt lgkmcnt(0)" ::: "memory"); SBAR(); } while (0)
; template <int B> __device__ __forceinline__ void vread(VSet& v, int vb) {
;   v.l0 = tr_read<v_rd_off(2 * B, 0, 0)>(vb); v.h0 = tr_read<v_rd_off(2 * B, 0, 1)>(vb); v.l1 = tr_read<v_rd_off(2 * B, 1, 0)>(vb); v.h1 = tr_read<v_rd_off(2 * B, 1, 1)>(vb);
;   v.l2 = tr_read<v_rd_off(2 * B + 1, 0, 0)>(vb); v.h2 = tr_read<v_rd_off(2 * B + 1, 0, 1)>(vb); v.l3 = tr_read<v_rd_off(2 * B + 1, 1, 0)>(vb); v.h3 = tr_read<v_rd_off(2 * B + 1, 1, 1)>(vb);
; }
; template <int B> __device__ __forceinline__ void pvmm(f32x4a (&o)[2][8], const VSet& v, const bf16x8 (&pa)[2][2]) {
;     ...
;   const bf16x8 v00 = PK(v.l0, v.h0), v01 = PK(v.l1, v.h1), v10 = PK(v.l2, v.h2), v11 = PK(v.l3, v.h3);
;   o[0][2 * B] = MM16(pa[0][0], v00, o[0][2 * B]); o[1][2 * B] = MM16(pa[1][0], v00, o[1][2 * B]); o[0][2 * B + 1] = MM16(pa[0][0], v10, o[0][2 * B + 1]); o[1][2 * B + 1] = MM16(pa[1][0], v10, o[1][2 * B + 1]);
;   o[0][2 * B] = MM16(pa[0][1], v01, o[0][2 * B]); o[1][2 * B] = MM16(pa[1][1], v01, o[1][2 * B]); o[0][2 * B + 1] = MM16(pa[0][1], v11, o[0][2 * B + 1]); o[1][2 * B + 1] = MM16(pa[1][1], v11, o[1][2 * B + 1]);
; __device__ __forceinline__ void attn_unit(int h, int qb_, const Tensors& T, char* lds, LASP unsigned char* ldsl, int tid_in) {
;     ...
;         LWAIT(); vread<1>(vb_, vbt); SBAR(); pvmm<0>(o, va, pa); SBAR();
;         LWAIT(); vread<2>(va, vbt); SBAR(); pvmm<1>(o, vb_, pa); SBAR();
;         LWAIT(); vread<3>(vb_, vbt); SBAR(); pvmm<2>(o, va, pa); SBAR();
;         LWAIT(); pvmm<3>(o, vb_, pa); SBAR();
;         __builtin_amdgcn_s_setprio(0);
.LBB0_576:
	s_waitcnt lgkmcnt(0)
	ds_read_b64_tr_b16 v[156:157], v238 offset:0x1000
	ds_read_b64_tr_b16 v[158:159], v238 offset:0x1200
	ds_read_b64_tr_b16 v[160:161], v238 offset:0x1400
	ds_read_b64_tr_b16 v[162:163], v238 offset:0x1600
	ds_read_b64_tr_b16 v[164:165], v238 offset:0x1800
	ds_read_b64_tr_b16 v[166:167], v238 offset:0x1a00
	ds_read_b64_tr_b16 v[168:169], v238 offset:0x1c00
	ds_read_b64_tr_b16 v[170:171], v238 offset:0x1e00
	v_mfma_f32_16x16x32_bf16 v[108:111], v[116:119], v[136:139], v[108:111]
	v_mfma_f32_16x16x32_bf16 v[44:47], v[124:127], v[136:139], v[44:47]
	v_mfma_f32_16x16x32_bf16 v[104:107], v[116:119], v[140:143], v[104:107]
	v_mfma_f32_16x16x32_bf16 v[40:43], v[124:127], v[140:143], v[40:43]
	v_mfma_f32_16x16x32_bf16 v[108:111], v[112:115], v[128:131], v[108:111]
	v_mfma_f32_16x16x32_bf16 v[44:47], v[120:123], v[128:131], v[44:47]
	v_mfma_f32_16x16x32_bf16 v[104:107], v[112:115], v[132:135], v[104:107]
	v_mfma_f32_16x16x32_bf16 v[40:43], v[120:123], v[132:135], v[40:43]
	s_waitcnt lgkmcnt(0)
	ds_read_b64_tr_b16 v[128:129], v238 offset:0x2000
	ds_read_b64_tr_b16 v[130:131], v238 offset:0x2200
	ds_read_b64_tr_b16 v[132:133], v238 offset:0x2400
	ds_read_b64_tr_b16 v[134:135], v238 offset:0x2600
	ds_read_b64_tr_b16 v[136:137], v238 offset:0x2800
	ds_read_b64_tr_b16 v[138:139], v238 offset:0x2a00
	ds_read_b64_tr_b16 v[140:141], v238 offset:0x2c00
	ds_read_b64_tr_b16 v[142:143], v238 offset:0x2e00
	v_mfma_f32_16x16x32_bf16 v[100:103], v[116:119], v[156:159], v[100:103]
	v_mfma_f32_16x16x32_bf16 v[36:39], v[124:127], v[156:159], v[36:39]
	v_mfma_f32_16x16x32_bf16 v[84:87], v[116:119], v[164:167], v[84:87]
	v_mfma_f32_16x16x32_bf16 v[32:35], v[124:127], v[164:167], v[32:35]
	v_mfma_f32_16x16x32_bf16 v[100:103], v[112:115], v[160:163], v[100:103]
	v_mfma_f32_16x16x32_bf16 v[36:39], v[120:123], v[160:163], v[36:39]
	v_mfma_f32_16x16x32_bf16 v[84:87], v[112:115], v[168:171], v[84:87]
	v_mfma_f32_16x16x32_bf16 v[32:35], v[120:123], v[168:171], v[32:35]
	s_waitcnt lgkmcnt(0)
	ds_read_b64_tr_b16 v[156:157], v238 offset:0x3000
	ds_read_b64_tr_b16 v[158:159], v238 offset:0x3200
	ds_read_b64_tr_b16 v[160:161], v238 offset:0x3400
	ds_read_b64_tr_b16 v[162:163], v238 offset:0x3600
	ds_read_b64_tr_b16 v[164:165], v238 offset:0x3800
	ds_read_b64_tr_b16 v[166:167], v238 offset:0x3a00
	ds_read_b64_tr_b16 v[168:169], v238 offset:0x3c00
	ds_read_b64_tr_b16 v[170:171], v238 offset:0x3e00
	v_mfma_f32_16x16x32_bf16 v[76:79], v[116:119], v[128:131], v[76:79]
	v_mfma_f32_16x16x32_bf16 v[28:31], v[124:127], v[128:131], v[28:31]
	v_mfma_f32_16x16x32_bf16 v[72:75], v[116:119], v[136:139], v[72:75]
	v_mfma_f32_16x16x32_bf16 v[24:27], v[124:127], v[136:139], v[24:27]
	v_mfma_f32_16x16x32_bf16 v[76:79], v[112:115], v[132:135], v[76:79]
	v_mfma_f32_16x16x32_bf16 v[28:31], v[120:123], v[132:135], v[28:31]
	v_mfma_f32_16x16x32_bf16 v[72:75], v[112:115], v[140:143], v[72:75]
	v_mfma_f32_16x16x32_bf16 v[24:27], v[120:123], v[140:143], v[24:27]
	s_waitcnt lgkmcnt(0)
	v_mfma_f32_16x16x32_bf16 v[52:55], v[116:119], v[156:159], v[52:55]
	v_mfma_f32_16x16x32_bf16 v[20:23], v[124:127], v[156:159], v[20:23]
	v_mfma_f32_16x16x32_bf16 v[48:51], v[116:119], v[164:167], v[48:51]
	v_mfma_f32_16x16x32_bf16 v[0:3], v[124:127], v[164:167], v[0:3]
	v_mfma_f32_16x16x32_bf16 v[52:55], v[112:115], v[160:163], v[52:55]
	v_mfma_f32_16x16x32_bf16 v[20:23], v[120:123], v[160:163], v[20:23]
	v_mfma_f32_16x16x32_bf16 v[48:51], v[112:115], v[168:171], v[48:51]
	v_mfma_f32_16x16x32_bf16 v[0:3], v[120:123], v[168:171], v[0:3]
	s_setprio 0
	s_andn2_b64 vcc, exec, s[28:29]
	s_cbranch_vccnz .LBB0_580
; __device__ __forceinline__ float sum_fq(float s) { return sum_xor32(sum_xor16(s)); }
; __device__ __forceinline__ unsigned cvtpk(float lo, float hi) { unsigned r; asm volatile("v_cvt_pk_bf16_f32 %0, %1, %2" : "=v"(r) : "v"(lo), "v"(hi)); return r; }
; __device__ __forceinline__ void attn_unit(int h, int qb_, const Tensors& T, char* lds, LASP unsigned char* ldsl, int tid_in) {
;     ...
;       if (t == NT - 1) {
;         l0 = pg8::sum_fq(l0); l1 = pg8::sum_fq(l1);
;         int ln; asm volatile("v_mbcnt_lo_u32_b32 %0, -1, 0\n\tv_mbcnt_hi_u32_b32 %0, -1, %0" : "=v"(ln));
;         if ((ln >> 4) == 0) { wsf[ln & 15] = l0; wsf[16 + (ln & 15)] = l1; }
;         asm volatile("s_waitcnt lgkmcnt(0)" ::: "memory");
; #pragma unroll
;         for (int qb = 0; qb < 2; ++qb) { const f32x4v lv = *(const f32x4v*)(wsf + 16 * qb + 4 * (ln >> 4));
;           const float r0 = __builtin_amdgcn_rcpf(lv[0]), r1 = __builtin_amdgcn_rcpf(lv[1]), r2 = __builtin_amdgcn_rcpf(lv[2]), r3 = __builtin_amdgcn_rcpf(lv[3]);
; #pragma unroll
;           for (int db = 0; db < 8; ++db) { op[qb][db][0] = cvtpk(o[qb][db][0] * r0, o[qb][db][1] * r1); op[qb][db][1] = cvtpk(o[qb][db][2] * r2, o[qb][db][3] * r3); o[qb][db] = (f32x4a){0.f, 0.f, 0.f, 0.f}; } }
;         asm volatile("s_waitcnt lgkmcnt(0)" ::: "memory");
;         l0 = 0.f; l1 = 0.f; }
	v_mov_b32_e32 v112, v155
	s_nop 1
	v_permlane16_swap_b32 v155, v112
	v_mov_b32_e32 v114, v154
	v_add_f32_e32 v112, v155, v112
	v_mov_b32_e32 v113, v112
	s_nop 1
	v_permlane32_swap_b32 v113, v112
	s_nop 1
	v_permlane16_swap_b32 v114, v154
	s_nop 0
	v_add_f32_e32 v115, v114, v154
	v_mov_b32_e32 v116, v115
	s_nop 1
	v_permlane32_swap_b32 v115, v116
	v_mbcnt_lo_u32_b32 v114, -1, 0
	v_mbcnt_hi_u32_b32 v114, -1, v114
	s_nop 0
	v_cmp_gt_u32_e32 vcc, 16, v114
	s_and_saveexec_b64 s[28:29], vcc
	v_add_f32_e32 v112, v113, v112
	v_add_f32_e32 v113, v115, v116
	v_lshl_add_u32 v115, v114, 2, s39
	ds_write2_b32 v115, v112, v113 offset1:16
	s_or_b64 exec, exec, s[28:29]
	v_and_b32_e32 v112, -16, v114
	s_waitcnt lgkmcnt(0)
	v_add_u32_e32 v116, s39, v112
	ds_read_b128 v[112:115], v116
	v_mov_b32_e32 v155, 0
	v_mov_b32_e32 v154, v155
	s_waitcnt lgkmcnt(0)
	v_rcp_f32_e32 v112, v112
	v_rcp_f32_e32 v113, v113
	v_rcp_f32_e32 v114, v114
	v_rcp_f32_e32 v115, v115
	v_mul_f32_e32 v104, v104, v112
	v_mul_f32_e32 v105, v105, v113
	v_mul_f32_e32 v100, v100, v112
	v_mul_f32_e32 v101, v101, v113
	v_mul_f32_e32 v84, v84, v112
	v_mul_f32_e32 v85, v85, v113
	v_mul_f32_e32 v76, v76, v112
	v_mul_f32_e32 v77, v77, v113
	v_mul_f32_e32 v72, v72, v112
	v_mul_f32_e32 v73, v73, v113
	v_mul_f32_e32 v52, v52, v112
	v_mul_f32_e32 v53, v53, v113
	v_mul_f32_e32 v48, v48, v112
	v_mul_f32_e32 v49, v49, v113
	v_mul_f32_e32 v108, v108, v112
	v_mul_f32_e32 v109, v109, v113
	v_mul_f32_e32 v110, v110, v114
	v_mul_f32_e32 v111, v111, v115
	v_cvt_pk_bf16_f32 v223, v108, v109
	v_cvt_pk_bf16_f32 v208, v110, v111
	v_cvt_pk_bf16_f32 v224, v104, v105
	v_mul_f32_e32 v104, v106, v114
	v_mul_f32_e32 v105, v107, v115
	v_cvt_pk_bf16_f32 v210, v104, v105
	v_cvt_pk_bf16_f32 v225, v100, v101
	v_mul_f32_e32 v100, v102, v114
	v_mul_f32_e32 v101, v103, v115
	v_cvt_pk_bf16_f32 v212, v100, v101
	v_cvt_pk_bf16_f32 v233, v84, v85
	v_mul_f32_e32 v84, v86, v114
	v_mul_f32_e32 v85, v87, v115
	v_cvt_pk_bf16_f32 v214, v84, v85
	v_cvt_pk_bf16_f32 v234, v76, v77
	v_mul_f32_e32 v76, v78, v114
	v_mul_f32_e32 v77, v79, v115
	v_cvt_pk_bf16_f32 v218, v76, v77
	v_cvt_pk_bf16_f32 v235, v72, v73
	v_mul_f32_e32 v72, v74, v114
	v_mul_f32_e32 v73, v75, v115
	v_cvt_pk_bf16_f32 v219, v72, v73
	v_cvt_pk_bf16_f32 v236, v52, v53
	v_mul_f32_e32 v52, v54, v114
	v_mul_f32_e32 v53, v55, v115
	v_cvt_pk_bf16_f32 v220, v52, v53
	v_cvt_pk_bf16_f32 v237, v48, v49
	v_mul_f32_e32 v48, v50, v114
	v_mul_f32_e32 v49, v51, v115
	v_cvt_pk_bf16_f32 v222, v48, v49
	ds_read_b128 v[48:51], v116 offset:64
	v_mov_b32_e32 v111, v155
	v_mov_b32_e32 v110, v155
	v_mov_b32_e32 v109, v155
	v_mov_b32_e32 v108, v155
	s_waitcnt lgkmcnt(0)
	v_rcp_f32_e32 v48, v48
	v_rcp_f32_e32 v49, v49
	v_rcp_f32_e32 v50, v50
	v_rcp_f32_e32 v51, v51
	v_mul_f32_e32 v44, v44, v48
	v_mul_f32_e32 v45, v45, v49
	v_mul_f32_e32 v40, v40, v48
	v_mul_f32_e32 v41, v41, v49
	v_mul_f32_e32 v36, v36, v48
	v_mul_f32_e32 v37, v37, v49
	v_mul_f32_e32 v32, v32, v48
	v_mul_f32_e32 v33, v33, v49
	v_mul_f32_e32 v28, v28, v48
	v_mul_f32_e32 v29, v29, v49
	v_mul_f32_e32 v24, v24, v48
	v_mul_f32_e32 v25, v25, v49
	v_mul_f32_e32 v20, v20, v48
	v_mul_f32_e32 v21, v21, v49
	v_mul_f32_e32 v0, v0, v48
	v_mul_f32_e32 v1, v1, v49
	v_cvt_pk_bf16_f32 v204, v44, v45
	v_mul_f32_e32 v44, v46, v50
	v_mul_f32_e32 v45, v47, v51
	v_cvt_pk_bf16_f32 v196, v44, v45
	v_cvt_pk_bf16_f32 v207, v40, v41
	v_mul_f32_e32 v40, v42, v50
	v_mul_f32_e32 v41, v43, v51
	v_cvt_pk_bf16_f32 v197, v40, v41
	v_cvt_pk_bf16_f32 v209, v36, v37
	v_mul_f32_e32 v36, v38, v50
	v_mul_f32_e32 v37, v39, v51
	v_cvt_pk_bf16_f32 v198, v36, v37
	v_cvt_pk_bf16_f32 v211, v32, v33
	v_mul_f32_e32 v32, v34, v50
	v_mul_f32_e32 v33, v35, v51
	v_cvt_pk_bf16_f32 v199, v32, v33
	v_cvt_pk_bf16_f32 v213, v28, v29
	v_mul_f32_e32 v28, v30, v50
	v_mul_f32_e32 v29, v31, v51
	v_cvt_pk_bf16_f32 v200, v28, v29
	v_cvt_pk_bf16_f32 v215, v24, v25
	v_mul_f32_e32 v24, v26, v50
	v_mul_f32_e32 v25, v27, v51
	v_cvt_pk_bf16_f32 v201, v24, v25
	v_cvt_pk_bf16_f32 v216, v20, v21
	v_mul_f32_e32 v20, v22, v50
	v_mul_f32_e32 v21, v23, v51
	v_cvt_pk_bf16_f32 v202, v20, v21
	v_cvt_pk_bf16_f32 v217, v0, v1
	v_mul_f32_e32 v0, v2, v50
	v_mul_f32_e32 v1, v3, v51
	v_cvt_pk_bf16_f32 v203, v0, v1
	s_waitcnt lgkmcnt(0)
	v_mov_b32_e32 v107, v155
	v_mov_b32_e32 v106, v155
	v_mov_b32_e32 v105, v155
	v_mov_b32_e32 v104, v155
	v_mov_b32_e32 v103, v155
	v_mov_b32_e32 v102, v155
	v_mov_b32_e32 v101, v155
	v_mov_b32_e32 v100, v155
	v_mov_b32_e32 v87, v155
	v_mov_b32_e32 v86, v155
	v_mov_b32_e32 v85, v155
	v_mov_b32_e32 v84, v155
	v_mov_b32_e32 v79, v155
	v_mov_b32_e32 v78, v155
	v_mov_b32_e32 v77, v155
	v_mov_b32_e32 v76, v155
	v_mov_b32_e32 v75, v155
	v_mov_b32_e32 v74, v155
	v_mov_b32_e32 v73, v155
	v_mov_b32_e32 v72, v155
	v_mov_b32_e32 v55, v155
	v_mov_b32_e32 v54, v155
	v_mov_b32_e32 v53, v155
	v_mov_b32_e32 v52, v155
	v_mov_b32_e32 v51, v155
	v_mov_b32_e32 v50, v155
	v_mov_b32_e32 v49, v155
	v_mov_b32_e32 v48, v155
	v_mov_b32_e32 v47, v155
	v_mov_b32_e32 v46, v155
	v_mov_b32_e32 v45, v155
	v_mov_b32_e32 v44, v155
	v_mov_b32_e32 v43, v155
	v_mov_b32_e32 v42, v155
	v_mov_b32_e32 v41, v155
	v_mov_b32_e32 v40, v155
	v_mov_b32_e32 v39, v155
	v_mov_b32_e32 v38, v155
	v_mov_b32_e32 v37, v155
	v_mov_b32_e32 v36, v155
	v_mov_b32_e32 v35, v155
	v_mov_b32_e32 v34, v155
	v_mov_b32_e32 v33, v155
	v_mov_b32_e32 v32, v155
	v_mov_b32_e32 v31, v155
	v_mov_b32_e32 v30, v155
	v_mov_b32_e32 v29, v155
	v_mov_b32_e32 v28, v155
	v_mov_b32_e32 v27, v155
	v_mov_b32_e32 v26, v155
	v_mov_b32_e32 v25, v155
	v_mov_b32_e32 v24, v155
	v_mov_b32_e32 v23, v155
	v_mov_b32_e32 v22, v155
	v_mov_b32_e32 v21, v155
	v_mov_b32_e32 v20, v155
	v_mov_b32_e32 v3, v155
	v_mov_b32_e32 v2, v155
	v_mov_b32_e32 v1, v155
	v_mov_b32_e32 v0, v155
